# in-proj GEMM loop: one s_barrier per superphase (halves place it at different points), MFMA prio 2 for waves 4-7, balanced LDS-DMA staging
# speedup vs baseline: 1.0119x; 1.0119x over previous
; #define PG8_STAGE(bufoff, gbase, voff) do { _Pragma("unroll") for (int _i = 0; _i < 2; ++_i) \
;         __builtin_amdgcn_global_load_lds((const unsigned*)((const char*)(gbase) + (voff)[_i]), (PG8_LAS unsigned*)(lds + (bufoff) + ldsw + _i * 8192), 16, 0, 0); } while (0)
; #define PG8_WAIT_V(n) asm volatile("s_waitcnt vmcnt(" #n ")" ::: "memory")
; #define PG8_BAR __builtin_amdgcn_s_barrier()
; template <class Epi, class Sched, bool ALIGN_EPI = false, bool SP2 = false>
; __device__ __forceinline__ void gemm_phase(PG8_LAS unsigned char* lds, const Gemm g, const Sched& S, const Epi& E) {
;     const int tid = threadIdx.x, wid = __builtin_amdgcn_readfirstlane(tid >> 6), lane = tid & 63, wr = wid >> 2, wc = wid & 3, fr = lane & 15, fq = lane >> 4;
;     const int K = g.K, nt = K / BK;
;     unsigned voffA[2], voffB[2];
; #pragma unroll
;     for (int i = 0; i < 2; ++i) { int R, C; stage_rc(tid * 16 + i * 8192, R, C); const int Rb = Epi::PERM ? ((R & ~31) + perm32(R & 31)) : R;
;         voffA[i] = (unsigned)(R * g.ld + C) * 2u; voffB[i] = (unsigned)(Rb * g.ld + C) * 2u; }
;     const size_t kstep = (size_t)(BK * 2);
;     const size_t hstep = (size_t)HALF * g.ld * 2;
;     const size_t tstep = 2 * hstep;
;     const unsigned ldsw = (unsigned)wid * 1024u;
;     const int aoff = lds_byte(wr * 64 + fr, fq * 8), boff = lds_byte(wc * 32 + fr, fq * 8);
;     ...
;     if constexpr (SP2) {
;         PG8_STAGE(PG8_SB(0, 0), cB, voffB); PG8_STAGE(PG8_SB(0, 1), cB + hstep, voffB); PG8_STAGE(PG8_SA(0, 0), cA, voffA); PG8_STAGE(PG8_SA(0, 1), cA + hstep, voffA);
;         if (wr == 1) PG8_BAR;
;         PG8_WAIT_V(2); PG8_BAR;
;         PG8_STAGE(PG8_SB(1, 0), cB + kstep, voffB); PG8_STAGE(PG8_SA(1, 0), cA + kstep, voffA); PG8_STAGE(PG8_SB(1, 1), cB + hstep + kstep, voffB);
;         PG8_WAIT_V(6); PG8_BAR;
.LBB0_338:
	s_lshl_b32 s1, s4, 5
	s_mov_b64 s[16:17], 0x80
	s_and_b32 s1, s1, 0x60
	s_add_i32 m0, s94, 0x18000
	v_lshl_add_u64 v[10:11], v[10:11], 0, s[16:17]
	s_lshl_b32 s0, s6, 13
	s_lshl_b32 s7, s1, 7
	s_ashr_i32 s24, s85, 31
	s_waitcnt vmcnt(2)
	s_barrier
	global_load_lds_dwordx4 v[10:11], off
	v_lshl_add_u64 v[8:9], v[8:9], 0, s[16:17]
	s_add_i32 m0, s94, 0x1a000
	s_add_i32 s25, s94, 0x8000
	s_add_i32 s82, s94, 0xa000
	global_load_lds_dwordx4 v[8:9], off
	v_lshl_add_u64 v[4:5], v[4:5], 0, s[16:17]
	s_mov_b32 m0, s25
	s_add_u32 s4, s90, 0x100080
	global_load_lds_dwordx4 v[4:5], off
	v_lshl_add_u64 v[4:5], v[6:7], 0, s[16:17]
	s_mov_b32 m0, s82
	s_addc_u32 s5, s91, 0
	global_load_lds_dwordx4 v[4:5], off
	s_add_i32 m0, s94, 0x1c000
	v_lshl_add_u64 v[4:5], s[4:5], 0, v[136:137]
	global_load_lds_dwordx4 v[4:5], off
	v_lshl_add_u64 v[4:5], s[4:5], 0, v[140:141]
	s_add_i32 m0, s94, 0x1e000
	v_lshlrev_b32_e32 v7, 2, v1
	global_load_lds_dwordx4 v[4:5], off
	s_add_u32 vcc_lo, s88, 0x100080
	s_addc_u32 vcc_hi, s89, 0
	s_add_i32 m0, s94, 0xc000
	s_nop 0
	global_load_lds_dwordx4 v134, vcc
	s_add_i32 m0, s94, 0xe000
	s_nop 0
	global_load_lds_dwordx4 v138, vcc
	v_lshrrev_b32_e32 v4, 1, v0
	v_and_b32_e32 v4, 24, v4
	v_lshlrev_b32_e32 v5, 1, v4
	v_lshl_or_b32 v6, v1, 6, v5
	v_and_b32_e32 v7, 32, v7
	v_bitop3_b32 v6, v6, s0, v7 bitop3:0xde
	v_lshlrev_b32_e32 v7, 6, v0
	s_movk_i32 s0, 0x3c0
	v_and_or_b32 v5, v7, s0, v5
	v_lshlrev_b32_e32 v7, 2, v0
	v_and_b32_e32 v7, 32, v7
	v_or_b32_e32 v168, s1, v4
	v_lshlrev_b32_e32 v4, 10, v0
	v_bitop3_b32 v167, s7, v5, v7 bitop3:0xf6
	v_and_b32_e32 v4, 0x60000, v4
	v_lshlrev_b32_e32 v5, 13, v13
	v_or3_b32 v4, v3, v4, v5
	s_ashr_i32 s83, s3, 31
	v_add_u32_e32 v142, v4, v12
	v_lshlrev_b32_e32 v4, 6, v14
	s_waitcnt vmcnt(8)
	s_cmpk_lt_u32 s2, 0x100
	v_and_b32_e32 v4, 0xe0000, v4
	s_cselect_b64 s[18:19], -1, 0
	v_or3_b32 v3, v3, v4, v5
	s_add_i32 s26, 0, 0x10000
	s_add_i32 s2, 0, 0x14000
	v_lshl_or_b32 v166, s6, 6, v1
	v_cmp_eq_u32_e64 s[4:5], 0, v1
	v_mov_b32_e32 v143, v2
	v_add_u32_e32 v144, v3, v12
	v_mov_b32_e32 v145, v2
	v_mov_b64_e32 v[146:147], 0x9ff
	v_add_u32_e32 v169, s26, v167
	v_add_u32_e32 v170, s2, v167
	v_add_u32_e32 v171, 0, v6
	s_lshl_b32 s20, s6, 2
	v_mov_b64_e32 v[148:149], 0xa3f
	v_mov_b32_e32 v172, 0x3e0293ee
	s_mov_b32 s46, 0
	s_barrier
	s_waitcnt vmcnt(0)
	s_branch .LBB0_341

;     __device__ __forceinline__ bool next(int i, Unit& u) const { const long L = (long)i * G + c; if (L >= nwg) return false; std_map((int)L, nM, nN, u, wgm); u.ui = i; return true; }
;     __device__ __forceinline__ bool next(int i, Unit& u) const { if (i >= 4) return false; const int x = c & 7, r = c >> 3; u.pm = 16 * i + 4 * (x >> 1) + (r & 3); u.pn = 8 * (x & 1) + (r >> 2); u.ui = i; return true; }
; #define PG8_STAGE(bufoff, gbase, voff) do { _Pragma("unroll") for (int _i = 0; _i < 2; ++_i) \
;         __builtin_amdgcn_global_load_lds((const unsigned*)((const char*)(gbase) + (voff)[_i]), (PG8_LAS unsigned*)(lds + (bufoff) + ldsw + _i * 8192), 16, 0, 0); } while (0)
; #define PG8_WAIT_V(n) asm volatile("s_waitcnt vmcnt(" #n ")" ::: "memory")
; #define PG8_WAIT_L(n) asm volatile("s_waitcnt lgkmcnt(" #n ")" ::: "memory")
; #define PG8_BAR __builtin_amdgcn_s_barrier()
; template <class Epi, class Sched, bool ALIGN_EPI = false, bool SP2 = false>
; __device__ __forceinline__ void gemm_phase(PG8_LAS unsigned char* lds, const Gemm g, const Sched& S, const Epi& E) {
;     ...
;         const bool has_next = S.next(ui + 1, nxt);
;         const char* nA = cA; const char* nB = cB; if (has_next) S.bases(nxt, g, tstep, nA, nB);
;         for (int t = 0; t < nt; t += 2) {
;             const bool last = (t == nt - 2);
;             const char* a1 = cA + (size_t)(t + 1) * kstep;
;             const char* a2 = last ? nA : cA + (size_t)(t + 2) * kstep; const char* b2 = last ? nB : cB + (size_t)(t + 2) * kstep;
;             const char* a3 = a2 + kstep; const char* b3 = b2 + kstep;
;             if (last && has_next) S.a_ready(nxt);
;             if constexpr (Epi::MIDK) { if (t == (nt >> 1)) { E.midk(acc, wr, fr); asm volatile("s_waitcnt lgkmcnt(0)" ::: "memory"); } }
;             if constexpr (SP2) {
;             PG8_LDB(B0, 0, 0); PG8_LDB(B1, 0, 1); PG8_SCHED; PG8_LDA(At, 0, 0); PG8_STAGE(PG8_SA(1, 1), a1 + hstep, voffA);
;             PG8_WAIT_V(8); PG8_WAIT_L(0); PG8_BAR; PG8_MMA(0, 0, At, B0); PG8_MMA(0, 1, At, B1); PG8_BAR; PG8_SCHED;
;     ...
; #pragma unroll
;         for (int a = 0; a < 2; ++a)
; #pragma unroll
;             for (int b = 0; b < 2; ++b)
; #pragma unroll
;                 for (int m = 0; m < 4; ++m)
; #pragma unroll
;                     for (int n = 0; n < 2; ++n) acc[a][b][m][n] = (f32x4){0.f, 0.f, 0.f, 0.f};
;         cur = nxt; cA = nA; cB = nB; ++ui;
.LBB0_348:
	s_add_u32 s88, s88, 0x100080
	s_addc_u32 s89, s89, 0
	s_add_u32 s9, s90, 0x100
	v_mov_b32_e32 v6, 0
	s_addc_u32 s21, s91, 0
	s_mov_b32 s23, -2
	v_mov_b32_e32 v7, v6
	v_mov_b32_e32 v8, v6
	v_mov_b32_e32 v9, v6
	v_mov_b32_e32 v10, v6
	v_mov_b32_e32 v11, v6
	v_mov_b32_e32 v12, v6
	v_mov_b32_e32 v13, v6
	v_mov_b32_e32 v22, v6
	v_mov_b32_e32 v23, v6
	v_mov_b32_e32 v24, v6
	v_mov_b32_e32 v25, v6
	v_mov_b32_e32 v26, v6
	v_mov_b32_e32 v27, v6
	v_mov_b32_e32 v28, v6
	v_mov_b32_e32 v29, v6
	v_mov_b32_e32 v54, v6
	v_mov_b32_e32 v55, v6
	v_mov_b32_e32 v56, v6
	v_mov_b32_e32 v57, v6
	v_mov_b32_e32 v58, v6
	v_mov_b32_e32 v59, v6
	v_mov_b32_e32 v60, v6
	v_mov_b32_e32 v61, v6
	v_mov_b32_e32 v70, v6
	v_mov_b32_e32 v71, v6
	v_mov_b32_e32 v72, v6
	v_mov_b32_e32 v73, v6
	v_mov_b32_e32 v74, v6
	v_mov_b32_e32 v75, v6
	v_mov_b32_e32 v76, v6
	v_mov_b32_e32 v77, v6
	v_mov_b32_e32 v14, v6
	v_mov_b32_e32 v15, v6
	v_mov_b32_e32 v16, v6
	v_mov_b32_e32 v17, v6
	v_mov_b32_e32 v18, v6
	v_mov_b32_e32 v19, v6
	v_mov_b32_e32 v20, v6
	v_mov_b32_e32 v21, v6
	v_mov_b32_e32 v34, v6
	v_mov_b32_e32 v35, v6
	v_mov_b32_e32 v36, v6
	v_mov_b32_e32 v37, v6
	v_mov_b32_e32 v42, v6
	v_mov_b32_e32 v43, v6
	v_mov_b32_e32 v44, v6
	v_mov_b32_e32 v45, v6
	v_mov_b32_e32 v62, v6
	v_mov_b32_e32 v63, v6
	v_mov_b32_e32 v64, v6
	v_mov_b32_e32 v65, v6
	v_mov_b32_e32 v66, v6
	v_mov_b32_e32 v67, v6
	v_mov_b32_e32 v68, v6
	v_mov_b32_e32 v69, v6
	v_mov_b32_e32 v78, v6
	v_mov_b32_e32 v79, v6
	v_mov_b32_e32 v80, v6
	v_mov_b32_e32 v81, v6
	v_mov_b32_e32 v82, v6
	v_mov_b32_e32 v83, v6
	v_mov_b32_e32 v84, v6
	v_mov_b32_e32 v85, v6
	v_mov_b32_e32 v86, v6
	v_mov_b32_e32 v87, v6
	v_mov_b32_e32 v88, v6
	v_mov_b32_e32 v89, v6
	v_mov_b32_e32 v90, v6
	v_mov_b32_e32 v91, v6
	v_mov_b32_e32 v92, v6
	v_mov_b32_e32 v93, v6
	v_mov_b32_e32 v102, v6
	v_mov_b32_e32 v103, v6
	v_mov_b32_e32 v104, v6
	v_mov_b32_e32 v105, v6
	v_mov_b32_e32 v106, v6
	v_mov_b32_e32 v107, v6
	v_mov_b32_e32 v108, v6
	v_mov_b32_e32 v109, v6
	v_mov_b32_e32 v118, v6
	v_mov_b32_e32 v119, v6
	v_mov_b32_e32 v120, v6
	v_mov_b32_e32 v121, v6
	v_mov_b32_e32 v122, v6
	v_mov_b32_e32 v123, v6
	v_mov_b32_e32 v124, v6
	v_mov_b32_e32 v125, v6
	v_mov_b32_e32 v46, v6
	v_mov_b32_e32 v47, v6
	v_mov_b32_e32 v48, v6
	v_mov_b32_e32 v49, v6
	v_mov_b32_e32 v50, v6
	v_mov_b32_e32 v51, v6
	v_mov_b32_e32 v52, v6
	v_mov_b32_e32 v53, v6
	v_mov_b32_e32 v94, v6
	v_mov_b32_e32 v95, v6
	v_mov_b32_e32 v96, v6
	v_mov_b32_e32 v97, v6
	v_mov_b32_e32 v98, v6
	v_mov_b32_e32 v99, v6
	v_mov_b32_e32 v100, v6
	v_mov_b32_e32 v101, v6
	v_mov_b32_e32 v110, v6
	v_mov_b32_e32 v111, v6
	v_mov_b32_e32 v112, v6
	v_mov_b32_e32 v113, v6
	v_mov_b32_e32 v114, v6
	v_mov_b32_e32 v115, v6
	v_mov_b32_e32 v116, v6
	v_mov_b32_e32 v117, v6
	v_mov_b32_e32 v126, v6
	v_mov_b32_e32 v127, v6
	v_mov_b32_e32 v128, v6
	v_mov_b32_e32 v129, v6
	v_mov_b32_e32 v130, v6
	v_mov_b32_e32 v131, v6
	v_mov_b32_e32 v132, v6
	v_mov_b32_e32 v133, v6
	v_mov_b32_e32 v30, v6
	v_mov_b32_e32 v31, v6
	v_mov_b32_e32 v32, v6
	v_mov_b32_e32 v33, v6
	v_mov_b32_e32 v38, v6
	v_mov_b32_e32 v39, v6
	v_mov_b32_e32 v40, v6
	v_mov_b32_e32 v41, v6
	s_cmp_lt_u32 s27, 0x1000
	s_cbranch_scc0 .Lip_h1
.LBB0_349:
	ds_read_b128 v[150:153], v169
	ds_read_b128 v[154:157], v169 offset:1024
	ds_read_b128 v[158:161], v169 offset:2048
	ds_read_b128 v[162:165], v169 offset:3072
	ds_read_b128 v[174:177], v170
	ds_read_b128 v[178:181], v170 offset:1024
	ds_read_b128 v[182:185], v170 offset:2048
	ds_read_b128 v[186:189], v170 offset:3072
	s_add_u32 s0, s88, 0xfff00080
	s_addc_u32 s1, s89, -1
	s_cmp_eq_u32 s23, 60
	s_cselect_b32 s93, s51, s1
	s_cselect_b32 s92, s50, s0
	s_cselect_b32 s91, s53, s21
	s_cselect_b32 s90, s52, s9
	ds_read_b128 v[190:193], v171
	ds_read_b128 v[196:199], v171 offset:1024
	ds_read_b128 v[200:203], v171 offset:2048
	ds_read_b128 v[204:207], v171 offset:3072
	ds_read_b128 v[208:211], v171 offset:4096
	ds_read_b128 v[212:215], v171 offset:5120
	ds_read_b128 v[220:223], v171 offset:6144
	ds_read_b128 v[224:227], v171 offset:7168
	s_add_u32 s0, s88, 0xfff00000
	s_addc_u32 s1, s89, -1
	s_add_i32 m0, s27, 0x8000
	s_nop 0
	global_load_lds_dwordx4 v134, s[0:1]
	s_add_i32 m0, s27, 0xa000
	s_nop 0
	global_load_lds_dwordx4 v138, s[0:1]
	s_add_i32 m0, s27, 0xc000
	s_nop 0
	global_load_lds_dwordx4 v134, s[88:89]
	s_add_i32 m0, s27, 0xe000
	s_nop 0
	global_load_lds_dwordx4 v138, s[88:89]
	s_waitcnt lgkmcnt(0)
	s_setprio 1
	v_mfma_f32_16x16x32_bf16 v[38:41], v[150:153], v[190:193], v[38:41]
	v_mfma_f32_16x16x32_bf16 v[30:33], v[158:161], v[190:193], v[30:33]
	v_mfma_f32_16x16x32_bf16 v[130:133], v[150:153], v[200:203], v[130:133]
	v_mfma_f32_16x16x32_bf16 v[126:129], v[158:161], v[200:203], v[126:129]
	v_mfma_f32_16x16x32_bf16 v[114:117], v[150:153], v[208:211], v[114:117]
	v_mfma_f32_16x16x32_bf16 v[110:113], v[158:161], v[208:211], v[110:113]
	v_mfma_f32_16x16x32_bf16 v[98:101], v[150:153], v[220:223], v[98:101]
	v_mfma_f32_16x16x32_bf16 v[94:97], v[158:161], v[220:223], v[94:97]
	v_mfma_f32_16x16x32_bf16 v[38:41], v[154:157], v[196:199], v[38:41]
	v_mfma_f32_16x16x32_bf16 v[30:33], v[162:165], v[196:199], v[30:33]
	v_mfma_f32_16x16x32_bf16 v[130:133], v[154:157], v[204:207], v[130:133]
	v_mfma_f32_16x16x32_bf16 v[126:129], v[162:165], v[204:207], v[126:129]
	v_mfma_f32_16x16x32_bf16 v[114:117], v[154:157], v[212:215], v[114:117]
	v_mfma_f32_16x16x32_bf16 v[110:113], v[162:165], v[212:215], v[110:113]
	v_mfma_f32_16x16x32_bf16 v[98:101], v[154:157], v[224:227], v[98:101]
	v_mfma_f32_16x16x32_bf16 v[94:97], v[162:165], v[224:227], v[94:97]
	v_mfma_f32_16x16x32_bf16 v[50:53], v[174:177], v[190:193], v[50:53]
	v_mfma_f32_16x16x32_bf16 v[46:49], v[182:185], v[190:193], v[46:49]
	v_mfma_f32_16x16x32_bf16 v[122:125], v[174:177], v[200:203], v[122:125]
	v_mfma_f32_16x16x32_bf16 v[118:121], v[182:185], v[200:203], v[118:121]
	v_mfma_f32_16x16x32_bf16 v[106:109], v[174:177], v[208:211], v[106:109]
	v_mfma_f32_16x16x32_bf16 v[102:105], v[182:185], v[208:211], v[102:105]
	v_mfma_f32_16x16x32_bf16 v[90:93], v[174:177], v[220:223], v[90:93]
	v_mfma_f32_16x16x32_bf16 v[86:89], v[182:185], v[220:223], v[86:89]
	v_mfma_f32_16x16x32_bf16 v[50:53], v[178:181], v[196:199], v[50:53]
	v_mfma_f32_16x16x32_bf16 v[46:49], v[186:189], v[196:199], v[46:49]
	v_mfma_f32_16x16x32_bf16 v[122:125], v[178:181], v[204:207], v[122:125]
	v_mfma_f32_16x16x32_bf16 v[118:121], v[186:189], v[204:207], v[118:121]
	v_mfma_f32_16x16x32_bf16 v[106:109], v[178:181], v[212:215], v[106:109]
	v_mfma_f32_16x16x32_bf16 v[102:105], v[186:189], v[212:215], v[102:105]
	v_mfma_f32_16x16x32_bf16 v[90:93], v[178:181], v[224:227], v[90:93]
	v_mfma_f32_16x16x32_bf16 v[86:89], v[186:189], v[224:227], v[86:89]
	s_setprio 0
	s_waitcnt vmcnt(8)
	s_barrier
; #define PG8_STAGE(bufoff, gbase, voff) do { _Pragma("unroll") for (int _i = 0; _i < 2; ++_i) \
;         __builtin_amdgcn_global_load_lds((const unsigned*)((const char*)(gbase) + (voff)[_i]), (PG8_LAS unsigned*)(lds + (bufoff) + ldsw + _i * 8192), 16, 0, 0); } while (0)
; #define PG8_LDA(dst, b, h) do { _Pragma("unroll") for (int m = 0; m < 4; ++m) _Pragma("unroll") for (int k = 0; k < 2; ++k) dst[m][k] = *(const PG8_LAS bf16x8*)(lds + PG8_SA(b, h) + aoff + m * 2048 + k * 1024); } while (0)
; #define PG8_LDB(dst, b, h) do { _Pragma("unroll") for (int n = 0; n < 2; ++n) _Pragma("unroll") for (int k = 0; k < 2; ++k) dst[n][k] = *(const PG8_LAS bf16x8*)(lds + PG8_SB(b, h) + boff + n * 2048 + k * 1024); } while (0)
; #define PG8_MMA(ai, bj, At, Bt) do { __builtin_amdgcn_s_setprio(1); _Pragma("unroll") for (int m = 0; m < 4; ++m) _Pragma("unroll") for (int n = 0; n < 2; ++n) _Pragma("unroll") for (int k = 0; k < 2; ++k) \
;         acc[ai][bj][m][n] = __builtin_amdgcn_mfma_f32_16x16x32_bf16(Bt[n][k], At[m][k], acc[ai][bj][m][n], 0, 0, 0); __builtin_amdgcn_s_setprio(0); } while (0)
; #define PG8_WAIT_V(n) asm volatile("s_waitcnt vmcnt(" #n ")" ::: "memory")
; #define PG8_WAIT_L(n) asm volatile("s_waitcnt lgkmcnt(" #n ")" ::: "memory")
; #define PG8_BAR __builtin_amdgcn_s_barrier()
; #define PG8_SCHED __builtin_amdgcn_sched_barrier(0)
; template <class Epi, class Sched, bool ALIGN_EPI = false, bool SP2 = false>
; __device__ __forceinline__ void gemm_phase(PG8_LAS unsigned char* lds, const Gemm g, const Sched& S, const Epi& E) {
;     ...
;             PG8_LDA(At, 0, 1); PG8_STAGE(PG8_SB(0, 0), b2, voffB); PG8_STAGE(PG8_SB(0, 1), b2 + hstep, voffB); PG8_STAGE(PG8_SA(0, 0), a2, voffA);
;             PG8_WAIT_V(8); PG8_WAIT_L(0); PG8_BAR; PG8_MMA(1, 0, At, B0); PG8_MMA(1, 1, At, B1); PG8_BAR; PG8_SCHED;
;             PG8_LDB(B0, 1, 0); PG8_LDB(B1, 1, 1); PG8_SCHED; PG8_LDA(At, 1, 0); PG8_STAGE(PG8_SA(0, 1), a2 + hstep, voffA);
;             PG8_WAIT_V(8); PG8_WAIT_L(0); PG8_BAR; PG8_MMA(0, 0, At, B0); PG8_MMA(0, 1, At, B1); PG8_BAR; PG8_SCHED;
	ds_read_b128 v[190:193], v171 offset:16384
	ds_read_b128 v[196:199], v171 offset:17408
	ds_read_b128 v[200:203], v171 offset:18432
	ds_read_b128 v[204:207], v171 offset:19456
	ds_read_b128 v[208:211], v171 offset:20480
	ds_read_b128 v[212:215], v171 offset:21504
	ds_read_b128 v[220:223], v171 offset:22528
	ds_read_b128 v[224:227], v171 offset:23552
	s_add_u32 vcc_lo, s90, 0x100000
	s_addc_u32 vcc_hi, s91, 0
	s_add_i32 m0, s27, 0x10000
	s_nop 0
	global_load_lds_dwordx4 v136, s[90:91]
	s_add_i32 m0, s27, 0x12000
	s_nop 0
	global_load_lds_dwordx4 v140, s[90:91]
	s_add_i32 m0, s27, 0x14000
	s_nop 0
	global_load_lds_dwordx4 v136, vcc
	s_add_i32 m0, s27, 0x16000
	s_nop 0
	global_load_lds_dwordx4 v140, vcc
	s_waitcnt lgkmcnt(0)
	s_setprio 1
	v_mfma_f32_16x16x32_bf16 v[82:85], v[150:153], v[190:193], v[82:85]
	v_mfma_f32_16x16x32_bf16 v[78:81], v[158:161], v[190:193], v[78:81]
	v_mfma_f32_16x16x32_bf16 v[66:69], v[150:153], v[200:203], v[66:69]
	v_mfma_f32_16x16x32_bf16 v[62:65], v[158:161], v[200:203], v[62:65]
	v_mfma_f32_16x16x32_bf16 v[42:45], v[150:153], v[208:211], v[42:45]
	v_mfma_f32_16x16x32_bf16 v[34:37], v[158:161], v[208:211], v[34:37]
	v_mfma_f32_16x16x32_bf16 v[18:21], v[150:153], v[220:223], v[18:21]
	v_mfma_f32_16x16x32_bf16 v[14:17], v[158:161], v[220:223], v[14:17]
	v_mfma_f32_16x16x32_bf16 v[82:85], v[154:157], v[196:199], v[82:85]
	v_mfma_f32_16x16x32_bf16 v[78:81], v[162:165], v[196:199], v[78:81]
	v_mfma_f32_16x16x32_bf16 v[66:69], v[154:157], v[204:207], v[66:69]
	v_mfma_f32_16x16x32_bf16 v[62:65], v[162:165], v[204:207], v[62:65]
	v_mfma_f32_16x16x32_bf16 v[42:45], v[154:157], v[212:215], v[42:45]
	v_mfma_f32_16x16x32_bf16 v[34:37], v[162:165], v[212:215], v[34:37]
	v_mfma_f32_16x16x32_bf16 v[18:21], v[154:157], v[224:227], v[18:21]
	v_mfma_f32_16x16x32_bf16 v[14:17], v[162:165], v[224:227], v[14:17]
	v_mfma_f32_16x16x32_bf16 v[74:77], v[174:177], v[190:193], v[74:77]
	v_mfma_f32_16x16x32_bf16 v[70:73], v[182:185], v[190:193], v[70:73]
	v_mfma_f32_16x16x32_bf16 v[58:61], v[174:177], v[200:203], v[58:61]
	v_mfma_f32_16x16x32_bf16 v[54:57], v[182:185], v[200:203], v[54:57]
	v_mfma_f32_16x16x32_bf16 v[26:29], v[174:177], v[208:211], v[26:29]
	v_mfma_f32_16x16x32_bf16 v[22:25], v[182:185], v[208:211], v[22:25]
	v_mfma_f32_16x16x32_bf16 v[10:13], v[174:177], v[220:223], v[10:13]
	v_mfma_f32_16x16x32_bf16 v[4:7], v[182:185], v[220:223], v[6:9]
	v_mfma_f32_16x16x32_bf16 v[74:77], v[178:181], v[196:199], v[74:77]
	v_mfma_f32_16x16x32_bf16 v[70:73], v[186:189], v[196:199], v[70:73]
	v_mfma_f32_16x16x32_bf16 v[58:61], v[178:181], v[204:207], v[58:61]
	v_mfma_f32_16x16x32_bf16 v[54:57], v[186:189], v[204:207], v[54:57]
	v_mfma_f32_16x16x32_bf16 v[26:29], v[178:181], v[212:215], v[26:29]
	v_mfma_f32_16x16x32_bf16 v[22:25], v[186:189], v[212:215], v[22:25]
	v_mfma_f32_16x16x32_bf16 v[10:13], v[178:181], v[224:227], v[10:13]
	v_mfma_f32_16x16x32_bf16 v[4:7], v[186:189], v[224:227], v[4:7]
	s_setprio 0
	s_waitcnt vmcnt(6)
	s_barrier
	s_add_i32 s0, 0, 0x18000
	v_add_u32_e32 v3, s0, v167
	s_add_i32 s1, 0, 0x1c000
	ds_read_b128 v[150:153], v3
	ds_read_b128 v[154:157], v3 offset:1024
	ds_read_b128 v[158:161], v3 offset:2048
	ds_read_b128 v[162:165], v3 offset:3072
	v_add_u32_e32 v3, s1, v167
	ds_read_b128 v[174:177], v3
	ds_read_b128 v[178:181], v3 offset:1024
	ds_read_b128 v[182:185], v3 offset:2048
	ds_read_b128 v[186:189], v3 offset:3072
	ds_read_b128 v[190:193], v171 offset:32768
	ds_read_b128 v[196:199], v171 offset:33792
	ds_read_b128 v[200:203], v171 offset:34816
	ds_read_b128 v[204:207], v171 offset:35840
	ds_read_b128 v[208:211], v171 offset:36864
	ds_read_b128 v[212:215], v171 offset:37888
	ds_read_b128 v[220:223], v171 offset:38912
	ds_read_b128 v[224:227], v171 offset:39936
	s_add_u32 vcc_lo, s92, 0x100000
	s_addc_u32 vcc_hi, s93, 0
	s_mov_b32 m0, s27
	s_nop 0
	global_load_lds_dwordx4 v134, s[92:93]
	s_add_i32 m0, s27, 0x2000
	s_nop 0
	global_load_lds_dwordx4 v138, s[92:93]
	s_add_i32 m0, s27, 0x4000
	s_nop 0
	global_load_lds_dwordx4 v134, vcc
	s_add_i32 m0, s27, 0x6000
	s_nop 0
	global_load_lds_dwordx4 v138, vcc
	s_waitcnt lgkmcnt(0)
	s_setprio 1
	v_mfma_f32_16x16x32_bf16 v[38:41], v[150:153], v[190:193], v[38:41]
	v_mfma_f32_16x16x32_bf16 v[30:33], v[158:161], v[190:193], v[30:33]
	v_mfma_f32_16x16x32_bf16 v[130:133], v[150:153], v[200:203], v[130:133]
	v_mfma_f32_16x16x32_bf16 v[126:129], v[158:161], v[200:203], v[126:129]
	v_mfma_f32_16x16x32_bf16 v[114:117], v[150:153], v[208:211], v[114:117]
	v_mfma_f32_16x16x32_bf16 v[110:113], v[158:161], v[208:211], v[110:113]
	v_mfma_f32_16x16x32_bf16 v[98:101], v[150:153], v[220:223], v[98:101]
	v_mfma_f32_16x16x32_bf16 v[94:97], v[158:161], v[220:223], v[94:97]
	v_mfma_f32_16x16x32_bf16 v[38:41], v[154:157], v[196:199], v[38:41]
	v_mfma_f32_16x16x32_bf16 v[30:33], v[162:165], v[196:199], v[30:33]
	v_mfma_f32_16x16x32_bf16 v[130:133], v[154:157], v[204:207], v[130:133]
	v_mfma_f32_16x16x32_bf16 v[126:129], v[162:165], v[204:207], v[126:129]
	v_mfma_f32_16x16x32_bf16 v[114:117], v[154:157], v[212:215], v[114:117]
	v_mfma_f32_16x16x32_bf16 v[110:113], v[162:165], v[212:215], v[110:113]
	v_mfma_f32_16x16x32_bf16 v[98:101], v[154:157], v[224:227], v[98:101]
	v_mfma_f32_16x16x32_bf16 v[94:97], v[162:165], v[224:227], v[94:97]
	v_mfma_f32_16x16x32_bf16 v[50:53], v[174:177], v[190:193], v[50:53]
	v_mfma_f32_16x16x32_bf16 v[46:49], v[182:185], v[190:193], v[46:49]
	v_mfma_f32_16x16x32_bf16 v[122:125], v[174:177], v[200:203], v[122:125]
	v_mfma_f32_16x16x32_bf16 v[118:121], v[182:185], v[200:203], v[118:121]
	v_mfma_f32_16x16x32_bf16 v[106:109], v[174:177], v[208:211], v[106:109]
	v_mfma_f32_16x16x32_bf16 v[102:105], v[182:185], v[208:211], v[102:105]
	v_mfma_f32_16x16x32_bf16 v[90:93], v[174:177], v[220:223], v[90:93]
	v_mfma_f32_16x16x32_bf16 v[86:89], v[182:185], v[220:223], v[86:89]
	v_mfma_f32_16x16x32_bf16 v[50:53], v[178:181], v[196:199], v[50:53]
	v_mfma_f32_16x16x32_bf16 v[46:49], v[186:189], v[196:199], v[46:49]
	v_mfma_f32_16x16x32_bf16 v[122:125], v[178:181], v[204:207], v[122:125]
	v_mfma_f32_16x16x32_bf16 v[118:121], v[186:189], v[204:207], v[118:121]
	v_mfma_f32_16x16x32_bf16 v[106:109], v[178:181], v[212:215], v[106:109]
	v_mfma_f32_16x16x32_bf16 v[102:105], v[186:189], v[212:215], v[102:105]
	v_mfma_f32_16x16x32_bf16 v[90:93], v[178:181], v[224:227], v[90:93]
	v_mfma_f32_16x16x32_bf16 v[86:89], v[186:189], v[224:227], v[86:89]
	s_setprio 0
	s_waitcnt vmcnt(8)
	s_barrier
; #define PG8_STAGE(bufoff, gbase, voff) do { _Pragma("unroll") for (int _i = 0; _i < 2; ++_i) \
;         __builtin_amdgcn_global_load_lds((const unsigned*)((const char*)(gbase) + (voff)[_i]), (PG8_LAS unsigned*)(lds + (bufoff) + ldsw + _i * 8192), 16, 0, 0); } while (0)
; #define PG8_LDA(dst, b, h) do { _Pragma("unroll") for (int m = 0; m < 4; ++m) _Pragma("unroll") for (int k = 0; k < 2; ++k) dst[m][k] = *(const PG8_LAS bf16x8*)(lds + PG8_SA(b, h) + aoff + m * 2048 + k * 1024); } while (0)
; #define PG8_LDB(dst, b, h) do { _Pragma("unroll") for (int n = 0; n < 2; ++n) _Pragma("unroll") for (int k = 0; k < 2; ++k) dst[n][k] = *(const PG8_LAS bf16x8*)(lds + PG8_SB(b, h) + boff + n * 2048 + k * 1024); } while (0)
; #define PG8_MMA(ai, bj, At, Bt) do { __builtin_amdgcn_s_setprio(1); _Pragma("unroll") for (int m = 0; m < 4; ++m) _Pragma("unroll") for (int n = 0; n < 2; ++n) _Pragma("unroll") for (int k = 0; k < 2; ++k) \
;         acc[ai][bj][m][n] = __builtin_amdgcn_mfma_f32_16x16x32_bf16(Bt[n][k], At[m][k], acc[ai][bj][m][n], 0, 0, 0); __builtin_amdgcn_s_setprio(0); } while (0)
; #define PG8_WAIT_V(n) asm volatile("s_waitcnt vmcnt(" #n ")" ::: "memory")
; #define PG8_WAIT_L(n) asm volatile("s_waitcnt lgkmcnt(" #n ")" ::: "memory")
; #define PG8_BAR __builtin_amdgcn_s_barrier()
; #define PG8_SCHED __builtin_amdgcn_sched_barrier(0)
; template <class Epi, class Sched, bool ALIGN_EPI = false, bool SP2 = false>
; __device__ __forceinline__ void gemm_phase(PG8_LAS unsigned char* lds, const Gemm g, const Sched& S, const Epi& E) {
;     ...
;             PG8_LDB(B0, 0, 0); PG8_LDB(B1, 0, 1); PG8_SCHED; PG8_LDA(At, 0, 0); PG8_STAGE(PG8_SA(1, 1), a1 + hstep, voffA);
;             PG8_WAIT_V(8); PG8_WAIT_L(0); PG8_BAR; PG8_MMA(0, 0, At, B0); PG8_MMA(0, 1, At, B1); PG8_BAR; PG8_SCHED;
;     ...
;             PG8_LDA(At, 1, 1); PG8_STAGE(PG8_SB(1, 0), b3, voffB); PG8_STAGE(PG8_SB(1, 1), b3 + hstep, voffB); PG8_STAGE(PG8_SA(1, 0), a3, voffA);
;             PG8_WAIT_V(8); PG8_WAIT_L(0); PG8_BAR; PG8_MMA(1, 0, At, B0); PG8_MMA(1, 1, At, B1); PG8_BAR; PG8_SCHED;
	ds_read_b128 v[190:193], v171 offset:49152
	ds_read_b128 v[196:199], v171 offset:50176
	ds_read_b128 v[200:203], v171 offset:51200
	ds_read_b128 v[204:207], v171 offset:52224
	ds_read_b128 v[208:211], v171 offset:53248
	ds_read_b128 v[212:215], v171 offset:54272
	ds_read_b128 v[220:223], v171 offset:55296
	ds_read_b128 v[224:227], v171 offset:56320
	s_add_u32 s0, s90, 0x80
	s_addc_u32 s1, s91, 0
	s_add_u32 vcc_lo, s0, 0x100000
	s_addc_u32 vcc_hi, s1, 0
	s_add_i32 m0, s27, 0x18000
	s_nop 0
	global_load_lds_dwordx4 v136, s[0:1]
	s_add_i32 m0, s27, 0x1a000
	s_nop 0
	global_load_lds_dwordx4 v140, s[0:1]
	s_add_i32 m0, s27, 0x1c000
	s_nop 0
	global_load_lds_dwordx4 v136, vcc
	s_add_i32 m0, s27, 0x1e000
	s_nop 0
	global_load_lds_dwordx4 v140, vcc
	s_waitcnt lgkmcnt(0)
	s_setprio 1
	v_mfma_f32_16x16x32_bf16 v[82:85], v[150:153], v[190:193], v[82:85]
	v_mfma_f32_16x16x32_bf16 v[78:81], v[158:161], v[190:193], v[78:81]
	v_mfma_f32_16x16x32_bf16 v[66:69], v[150:153], v[200:203], v[66:69]
	v_mfma_f32_16x16x32_bf16 v[62:65], v[158:161], v[200:203], v[62:65]
	v_mfma_f32_16x16x32_bf16 v[42:45], v[150:153], v[208:211], v[42:45]
	v_mfma_f32_16x16x32_bf16 v[34:37], v[158:161], v[208:211], v[34:37]
	v_mfma_f32_16x16x32_bf16 v[18:21], v[150:153], v[220:223], v[18:21]
	v_mfma_f32_16x16x32_bf16 v[14:17], v[158:161], v[220:223], v[14:17]
	v_mfma_f32_16x16x32_bf16 v[82:85], v[154:157], v[196:199], v[82:85]
	v_mfma_f32_16x16x32_bf16 v[78:81], v[162:165], v[196:199], v[78:81]
	v_mfma_f32_16x16x32_bf16 v[66:69], v[154:157], v[204:207], v[66:69]
	v_mfma_f32_16x16x32_bf16 v[62:65], v[162:165], v[204:207], v[62:65]
	v_mfma_f32_16x16x32_bf16 v[42:45], v[154:157], v[212:215], v[42:45]
	v_mfma_f32_16x16x32_bf16 v[34:37], v[162:165], v[212:215], v[34:37]
	v_mfma_f32_16x16x32_bf16 v[18:21], v[154:157], v[224:227], v[18:21]
	v_mfma_f32_16x16x32_bf16 v[14:17], v[162:165], v[224:227], v[14:17]
	v_mfma_f32_16x16x32_bf16 v[74:77], v[174:177], v[190:193], v[74:77]
	v_mfma_f32_16x16x32_bf16 v[70:73], v[182:185], v[190:193], v[70:73]
	v_mfma_f32_16x16x32_bf16 v[58:61], v[174:177], v[200:203], v[58:61]
	v_mfma_f32_16x16x32_bf16 v[54:57], v[182:185], v[200:203], v[54:57]
	v_mfma_f32_16x16x32_bf16 v[26:29], v[174:177], v[208:211], v[26:29]
	v_mfma_f32_16x16x32_bf16 v[22:25], v[182:185], v[208:211], v[22:25]
	v_mfma_f32_16x16x32_bf16 v[8:11], v[174:177], v[220:223], v[10:13]
	v_mfma_f32_16x16x32_bf16 v[4:7], v[182:185], v[220:223], v[4:7]
	v_mfma_f32_16x16x32_bf16 v[74:77], v[178:181], v[196:199], v[74:77]
	v_mfma_f32_16x16x32_bf16 v[70:73], v[186:189], v[196:199], v[70:73]
	v_mfma_f32_16x16x32_bf16 v[58:61], v[178:181], v[204:207], v[58:61]
	v_mfma_f32_16x16x32_bf16 v[54:57], v[186:189], v[204:207], v[54:57]
	v_mfma_f32_16x16x32_bf16 v[26:29], v[178:181], v[212:215], v[26:29]
	v_mfma_f32_16x16x32_bf16 v[22:25], v[186:189], v[212:215], v[22:25]
	v_mfma_f32_16x16x32_bf16 v[10:13], v[178:181], v[224:227], v[8:11]
	v_mfma_f32_16x16x32_bf16 v[6:9], v[186:189], v[224:227], v[4:7]
	s_setprio 0
	s_waitcnt vmcnt(6)
	s_barrier
	s_add_i32 s23, s23, 2
	s_add_u32 s88, s88, 0x100
	s_addc_u32 s89, s89, 0
	s_add_u32 s9, s9, 0x100
	s_addc_u32 s21, s21, 0
	s_cmp_gt_u32 s23, 61
	s_cbranch_scc0 .LBB0_349
	s_branch .Lip_exit
.Lip_h1:
	ds_read_b128 v[150:153], v169
	ds_read_b128 v[154:157], v169 offset:1024
	ds_read_b128 v[158:161], v169 offset:2048
	ds_read_b128 v[162:165], v169 offset:3072
	ds_read_b128 v[174:177], v170
	ds_read_b128 v[178:181], v170 offset:1024
	ds_read_b128 v[182:185], v170 offset:2048
	ds_read_b128 v[186:189], v170 offset:3072
	s_add_u32 s0, s88, 0xfff00080
	s_addc_u32 s1, s89, -1
	s_cmp_eq_u32 s23, 60
	s_cselect_b32 s93, s51, s1
	s_cselect_b32 s92, s50, s0
	s_cselect_b32 s91, s53, s21
	s_cselect_b32 s90, s52, s9
	ds_read_b128 v[190:193], v171
	ds_read_b128 v[196:199], v171 offset:1024
	ds_read_b128 v[200:203], v171 offset:2048
	ds_read_b128 v[204:207], v171 offset:3072
	ds_read_b128 v[208:211], v171 offset:4096
	ds_read_b128 v[212:215], v171 offset:5120
	ds_read_b128 v[220:223], v171 offset:6144
	ds_read_b128 v[224:227], v171 offset:7168
	s_add_u32 s0, s88, 0xfff00000
	s_addc_u32 s1, s89, -1
	s_add_i32 m0, s27, 0x8000
	s_nop 0
	global_load_lds_dwordx4 v134, s[0:1]
	s_add_i32 m0, s27, 0xa000
	s_nop 0
	global_load_lds_dwordx4 v138, s[0:1]
	s_add_i32 m0, s27, 0xc000
	s_nop 0
	global_load_lds_dwordx4 v134, s[88:89]
	s_add_i32 m0, s27, 0xe000
	s_nop 0
	global_load_lds_dwordx4 v138, s[88:89]
	s_sleep 2
	s_waitcnt lgkmcnt(0)
	s_waitcnt vmcnt(8)
	s_barrier
; #define PG8_STAGE(bufoff, gbase, voff) do { _Pragma("unroll") for (int _i = 0; _i < 2; ++_i) \
;         __builtin_amdgcn_global_load_lds((const unsigned*)((const char*)(gbase) + (voff)[_i]), (PG8_LAS unsigned*)(lds + (bufoff) + ldsw + _i * 8192), 16, 0, 0); } while (0)
; #define PG8_LDA(dst, b, h) do { _Pragma("unroll") for (int m = 0; m < 4; ++m) _Pragma("unroll") for (int k = 0; k < 2; ++k) dst[m][k] = *(const PG8_LAS bf16x8*)(lds + PG8_SA(b, h) + aoff + m * 2048 + k * 1024); } while (0)
; #define PG8_LDB(dst, b, h) do { _Pragma("unroll") for (int n = 0; n < 2; ++n) _Pragma("unroll") for (int k = 0; k < 2; ++k) dst[n][k] = *(const PG8_LAS bf16x8*)(lds + PG8_SB(b, h) + boff + n * 2048 + k * 1024); } while (0)
; #define PG8_MMA(ai, bj, At, Bt) do { __builtin_amdgcn_s_setprio(1); _Pragma("unroll") for (int m = 0; m < 4; ++m) _Pragma("unroll") for (int n = 0; n < 2; ++n) _Pragma("unroll") for (int k = 0; k < 2; ++k) \
;         acc[ai][bj][m][n] = __builtin_amdgcn_mfma_f32_16x16x32_bf16(Bt[n][k], At[m][k], acc[ai][bj][m][n], 0, 0, 0); __builtin_amdgcn_s_setprio(0); } while (0)
; #define PG8_WAIT_V(n) asm volatile("s_waitcnt vmcnt(" #n ")" ::: "memory")
; #define PG8_WAIT_L(n) asm volatile("s_waitcnt lgkmcnt(" #n ")" ::: "memory")
; #define PG8_BAR __builtin_amdgcn_s_barrier()
; #define PG8_SCHED __builtin_amdgcn_sched_barrier(0)
; template <class Epi, class Sched, bool ALIGN_EPI = false, bool SP2 = false>
; __device__ __forceinline__ void gemm_phase(PG8_LAS unsigned char* lds, const Gemm g, const Sched& S, const Epi& E) {
;     ...
;             PG8_WAIT_V(8); PG8_WAIT_L(0); PG8_BAR; PG8_MMA(0, 0, At, B0); PG8_MMA(0, 1, At, B1); PG8_BAR; PG8_SCHED;
;             PG8_LDA(At, 0, 1); PG8_STAGE(PG8_SB(0, 0), b2, voffB); PG8_STAGE(PG8_SB(0, 1), b2 + hstep, voffB); PG8_STAGE(PG8_SA(0, 0), a2, voffA);
;             PG8_WAIT_V(8); PG8_WAIT_L(0); PG8_BAR; PG8_MMA(1, 0, At, B0); PG8_MMA(1, 1, At, B1); PG8_BAR; PG8_SCHED;
;             PG8_LDB(B0, 1, 0); PG8_LDB(B1, 1, 1); PG8_SCHED; PG8_LDA(At, 1, 0); PG8_STAGE(PG8_SA(0, 1), a2 + hstep, voffA);
;             PG8_WAIT_V(8); PG8_WAIT_L(0); PG8_BAR; PG8_MMA(0, 0, At, B0); PG8_MMA(0, 1, At, B1); PG8_BAR; PG8_SCHED;
	s_setprio 2
	v_mfma_f32_16x16x32_bf16 v[38:41], v[150:153], v[190:193], v[38:41]
	v_mfma_f32_16x16x32_bf16 v[30:33], v[158:161], v[190:193], v[30:33]
	v_mfma_f32_16x16x32_bf16 v[130:133], v[150:153], v[200:203], v[130:133]
	v_mfma_f32_16x16x32_bf16 v[126:129], v[158:161], v[200:203], v[126:129]
	v_mfma_f32_16x16x32_bf16 v[114:117], v[150:153], v[208:211], v[114:117]
	v_mfma_f32_16x16x32_bf16 v[110:113], v[158:161], v[208:211], v[110:113]
	v_mfma_f32_16x16x32_bf16 v[98:101], v[150:153], v[220:223], v[98:101]
	v_mfma_f32_16x16x32_bf16 v[94:97], v[158:161], v[220:223], v[94:97]
	v_mfma_f32_16x16x32_bf16 v[38:41], v[154:157], v[196:199], v[38:41]
	v_mfma_f32_16x16x32_bf16 v[30:33], v[162:165], v[196:199], v[30:33]
	v_mfma_f32_16x16x32_bf16 v[130:133], v[154:157], v[204:207], v[130:133]
	v_mfma_f32_16x16x32_bf16 v[126:129], v[162:165], v[204:207], v[126:129]
	v_mfma_f32_16x16x32_bf16 v[114:117], v[154:157], v[212:215], v[114:117]
	v_mfma_f32_16x16x32_bf16 v[110:113], v[162:165], v[212:215], v[110:113]
	v_mfma_f32_16x16x32_bf16 v[98:101], v[154:157], v[224:227], v[98:101]
	v_mfma_f32_16x16x32_bf16 v[94:97], v[162:165], v[224:227], v[94:97]
	v_mfma_f32_16x16x32_bf16 v[50:53], v[174:177], v[190:193], v[50:53]
	v_mfma_f32_16x16x32_bf16 v[46:49], v[182:185], v[190:193], v[46:49]
	v_mfma_f32_16x16x32_bf16 v[122:125], v[174:177], v[200:203], v[122:125]
	v_mfma_f32_16x16x32_bf16 v[118:121], v[182:185], v[200:203], v[118:121]
	v_mfma_f32_16x16x32_bf16 v[106:109], v[174:177], v[208:211], v[106:109]
	v_mfma_f32_16x16x32_bf16 v[102:105], v[182:185], v[208:211], v[102:105]
	v_mfma_f32_16x16x32_bf16 v[90:93], v[174:177], v[220:223], v[90:93]
	v_mfma_f32_16x16x32_bf16 v[86:89], v[182:185], v[220:223], v[86:89]
	v_mfma_f32_16x16x32_bf16 v[50:53], v[178:181], v[196:199], v[50:53]
	v_mfma_f32_16x16x32_bf16 v[46:49], v[186:189], v[196:199], v[46:49]
	v_mfma_f32_16x16x32_bf16 v[122:125], v[178:181], v[204:207], v[122:125]
	v_mfma_f32_16x16x32_bf16 v[118:121], v[186:189], v[204:207], v[118:121]
	v_mfma_f32_16x16x32_bf16 v[106:109], v[178:181], v[212:215], v[106:109]
	v_mfma_f32_16x16x32_bf16 v[102:105], v[186:189], v[212:215], v[102:105]
	v_mfma_f32_16x16x32_bf16 v[90:93], v[178:181], v[224:227], v[90:93]
	v_mfma_f32_16x16x32_bf16 v[86:89], v[186:189], v[224:227], v[86:89]
	s_setprio 0
	ds_read_b128 v[190:193], v171 offset:16384
	ds_read_b128 v[196:199], v171 offset:17408
	ds_read_b128 v[200:203], v171 offset:18432
	ds_read_b128 v[204:207], v171 offset:19456
	ds_read_b128 v[208:211], v171 offset:20480
	ds_read_b128 v[212:215], v171 offset:21504
	ds_read_b128 v[220:223], v171 offset:22528
	ds_read_b128 v[224:227], v171 offset:23552
	s_add_u32 vcc_lo, s90, 0x100000
	s_addc_u32 vcc_hi, s91, 0
	s_add_i32 m0, s27, 0x10000
	s_nop 0
	global_load_lds_dwordx4 v136, s[90:91]
	s_add_i32 m0, s27, 0x12000
	s_nop 0
	global_load_lds_dwordx4 v140, s[90:91]
	s_add_i32 m0, s27, 0x14000
	s_nop 0
	global_load_lds_dwordx4 v136, vcc
	s_add_i32 m0, s27, 0x16000
	s_nop 0
	global_load_lds_dwordx4 v140, vcc
	s_sleep 2
	s_waitcnt lgkmcnt(0)
	s_waitcnt vmcnt(6)
	s_barrier
	s_setprio 2
	v_mfma_f32_16x16x32_bf16 v[82:85], v[150:153], v[190:193], v[82:85]
	v_mfma_f32_16x16x32_bf16 v[78:81], v[158:161], v[190:193], v[78:81]
	v_mfma_f32_16x16x32_bf16 v[66:69], v[150:153], v[200:203], v[66:69]
	v_mfma_f32_16x16x32_bf16 v[62:65], v[158:161], v[200:203], v[62:65]
	v_mfma_f32_16x16x32_bf16 v[42:45], v[150:153], v[208:211], v[42:45]
	v_mfma_f32_16x16x32_bf16 v[34:37], v[158:161], v[208:211], v[34:37]
	v_mfma_f32_16x16x32_bf16 v[18:21], v[150:153], v[220:223], v[18:21]
	v_mfma_f32_16x16x32_bf16 v[14:17], v[158:161], v[220:223], v[14:17]
	v_mfma_f32_16x16x32_bf16 v[82:85], v[154:157], v[196:199], v[82:85]
	v_mfma_f32_16x16x32_bf16 v[78:81], v[162:165], v[196:199], v[78:81]
	v_mfma_f32_16x16x32_bf16 v[66:69], v[154:157], v[204:207], v[66:69]
	v_mfma_f32_16x16x32_bf16 v[62:65], v[162:165], v[204:207], v[62:65]
	v_mfma_f32_16x16x32_bf16 v[42:45], v[154:157], v[212:215], v[42:45]
	v_mfma_f32_16x16x32_bf16 v[34:37], v[162:165], v[212:215], v[34:37]
	v_mfma_f32_16x16x32_bf16 v[18:21], v[154:157], v[224:227], v[18:21]
	v_mfma_f32_16x16x32_bf16 v[14:17], v[162:165], v[224:227], v[14:17]
	v_mfma_f32_16x16x32_bf16 v[74:77], v[174:177], v[190:193], v[74:77]
	v_mfma_f32_16x16x32_bf16 v[70:73], v[182:185], v[190:193], v[70:73]
	v_mfma_f32_16x16x32_bf16 v[58:61], v[174:177], v[200:203], v[58:61]
	v_mfma_f32_16x16x32_bf16 v[54:57], v[182:185], v[200:203], v[54:57]
	v_mfma_f32_16x16x32_bf16 v[26:29], v[174:177], v[208:211], v[26:29]
	v_mfma_f32_16x16x32_bf16 v[22:25], v[182:185], v[208:211], v[22:25]
	v_mfma_f32_16x16x32_bf16 v[10:13], v[174:177], v[220:223], v[10:13]
	v_mfma_f32_16x16x32_bf16 v[4:7], v[182:185], v[220:223], v[6:9]
	v_mfma_f32_16x16x32_bf16 v[74:77], v[178:181], v[196:199], v[74:77]
	v_mfma_f32_16x16x32_bf16 v[70:73], v[186:189], v[196:199], v[70:73]
	v_mfma_f32_16x16x32_bf16 v[58:61], v[178:181], v[204:207], v[58:61]
	v_mfma_f32_16x16x32_bf16 v[54:57], v[186:189], v[204:207], v[54:57]
	v_mfma_f32_16x16x32_bf16 v[26:29], v[178:181], v[212:215], v[26:29]
	v_mfma_f32_16x16x32_bf16 v[22:25], v[186:189], v[212:215], v[22:25]
	v_mfma_f32_16x16x32_bf16 v[10:13], v[178:181], v[224:227], v[10:13]
	v_mfma_f32_16x16x32_bf16 v[4:7], v[186:189], v[224:227], v[4:7]
	s_setprio 0
	s_add_i32 s0, 0, 0x18000
	v_add_u32_e32 v3, s0, v167
	s_add_i32 s1, 0, 0x1c000
	ds_read_b128 v[150:153], v3
	ds_read_b128 v[154:157], v3 offset:1024
	ds_read_b128 v[158:161], v3 offset:2048
	ds_read_b128 v[162:165], v3 offset:3072
	v_add_u32_e32 v3, s1, v167
	ds_read_b128 v[174:177], v3
	ds_read_b128 v[178:181], v3 offset:1024
	ds_read_b128 v[182:185], v3 offset:2048
	ds_read_b128 v[186:189], v3 offset:3072
	ds_read_b128 v[190:193], v171 offset:32768
	ds_read_b128 v[196:199], v171 offset:33792
	ds_read_b128 v[200:203], v171 offset:34816
	ds_read_b128 v[204:207], v171 offset:35840
	ds_read_b128 v[208:211], v171 offset:36864
	ds_read_b128 v[212:215], v171 offset:37888
	ds_read_b128 v[220:223], v171 offset:38912
	ds_read_b128 v[224:227], v171 offset:39936
	s_add_u32 vcc_lo, s92, 0x100000
	s_addc_u32 vcc_hi, s93, 0
	s_mov_b32 m0, s27
	s_nop 0
	global_load_lds_dwordx4 v134, s[92:93]
	s_add_i32 m0, s27, 0x2000
	s_nop 0
	global_load_lds_dwordx4 v138, s[92:93]
	s_add_i32 m0, s27, 0x4000
	s_nop 0
	global_load_lds_dwordx4 v134, vcc
	s_add_i32 m0, s27, 0x6000
	s_nop 0
	global_load_lds_dwordx4 v138, vcc
	s_sleep 2
	s_waitcnt lgkmcnt(0)
	s_waitcnt vmcnt(8)
	s_barrier
; #define PG8_STAGE(bufoff, gbase, voff) do { _Pragma("unroll") for (int _i = 0; _i < 2; ++_i) \
;         __builtin_amdgcn_global_load_lds((const unsigned*)((const char*)(gbase) + (voff)[_i]), (PG8_LAS unsigned*)(lds + (bufoff) + ldsw + _i * 8192), 16, 0, 0); } while (0)
; #define PG8_LDA(dst, b, h) do { _Pragma("unroll") for (int m = 0; m < 4; ++m) _Pragma("unroll") for (int k = 0; k < 2; ++k) dst[m][k] = *(const PG8_LAS bf16x8*)(lds + PG8_SA(b, h) + aoff + m * 2048 + k * 1024); } while (0)
; #define PG8_MMA(ai, bj, At, Bt) do { __builtin_amdgcn_s_setprio(1); _Pragma("unroll") for (int m = 0; m < 4; ++m) _Pragma("unroll") for (int n = 0; n < 2; ++n) _Pragma("unroll") for (int k = 0; k < 2; ++k) \
;         acc[ai][bj][m][n] = __builtin_amdgcn_mfma_f32_16x16x32_bf16(Bt[n][k], At[m][k], acc[ai][bj][m][n], 0, 0, 0); __builtin_amdgcn_s_setprio(0); } while (0)
; #define PG8_WAIT_V(n) asm volatile("s_waitcnt vmcnt(" #n ")" ::: "memory")
; #define PG8_WAIT_L(n) asm volatile("s_waitcnt lgkmcnt(" #n ")" ::: "memory")
; #define PG8_BAR __builtin_amdgcn_s_barrier()
; #define PG8_SCHED __builtin_amdgcn_sched_barrier(0)
; template <class Epi, class Sched, bool ALIGN_EPI = false, bool SP2 = false>
; __device__ __forceinline__ void gemm_phase(PG8_LAS unsigned char* lds, const Gemm g, const Sched& S, const Epi& E) {
;     ...
;             PG8_WAIT_V(8); PG8_WAIT_L(0); PG8_BAR; PG8_MMA(0, 0, At, B0); PG8_MMA(0, 1, At, B1); PG8_BAR; PG8_SCHED;
;             PG8_LDA(At, 1, 1); PG8_STAGE(PG8_SB(1, 0), b3, voffB); PG8_STAGE(PG8_SB(1, 1), b3 + hstep, voffB); PG8_STAGE(PG8_SA(1, 0), a3, voffA);
;             PG8_WAIT_V(8); PG8_WAIT_L(0); PG8_BAR; PG8_MMA(1, 0, At, B0); PG8_MMA(1, 1, At, B1); PG8_BAR; PG8_SCHED;
;     ...
;         if constexpr (ALIGN_EPI) { if (wr == 0) PG8_BAR; }
	s_setprio 2
	v_mfma_f32_16x16x32_bf16 v[38:41], v[150:153], v[190:193], v[38:41]
	v_mfma_f32_16x16x32_bf16 v[30:33], v[158:161], v[190:193], v[30:33]
	v_mfma_f32_16x16x32_bf16 v[130:133], v[150:153], v[200:203], v[130:133]
	v_mfma_f32_16x16x32_bf16 v[126:129], v[158:161], v[200:203], v[126:129]
	v_mfma_f32_16x16x32_bf16 v[114:117], v[150:153], v[208:211], v[114:117]
	v_mfma_f32_16x16x32_bf16 v[110:113], v[158:161], v[208:211], v[110:113]
	v_mfma_f32_16x16x32_bf16 v[98:101], v[150:153], v[220:223], v[98:101]
	v_mfma_f32_16x16x32_bf16 v[94:97], v[158:161], v[220:223], v[94:97]
	v_mfma_f32_16x16x32_bf16 v[38:41], v[154:157], v[196:199], v[38:41]
	v_mfma_f32_16x16x32_bf16 v[30:33], v[162:165], v[196:199], v[30:33]
	v_mfma_f32_16x16x32_bf16 v[130:133], v[154:157], v[204:207], v[130:133]
	v_mfma_f32_16x16x32_bf16 v[126:129], v[162:165], v[204:207], v[126:129]
	v_mfma_f32_16x16x32_bf16 v[114:117], v[154:157], v[212:215], v[114:117]
	v_mfma_f32_16x16x32_bf16 v[110:113], v[162:165], v[212:215], v[110:113]
	v_mfma_f32_16x16x32_bf16 v[98:101], v[154:157], v[224:227], v[98:101]
	v_mfma_f32_16x16x32_bf16 v[94:97], v[162:165], v[224:227], v[94:97]
	v_mfma_f32_16x16x32_bf16 v[50:53], v[174:177], v[190:193], v[50:53]
	v_mfma_f32_16x16x32_bf16 v[46:49], v[182:185], v[190:193], v[46:49]
	v_mfma_f32_16x16x32_bf16 v[122:125], v[174:177], v[200:203], v[122:125]
	v_mfma_f32_16x16x32_bf16 v[118:121], v[182:185], v[200:203], v[118:121]
	v_mfma_f32_16x16x32_bf16 v[106:109], v[174:177], v[208:211], v[106:109]
	v_mfma_f32_16x16x32_bf16 v[102:105], v[182:185], v[208:211], v[102:105]
	v_mfma_f32_16x16x32_bf16 v[90:93], v[174:177], v[220:223], v[90:93]
	v_mfma_f32_16x16x32_bf16 v[86:89], v[182:185], v[220:223], v[86:89]
	v_mfma_f32_16x16x32_bf16 v[50:53], v[178:181], v[196:199], v[50:53]
	v_mfma_f32_16x16x32_bf16 v[46:49], v[186:189], v[196:199], v[46:49]
	v_mfma_f32_16x16x32_bf16 v[122:125], v[178:181], v[204:207], v[122:125]
	v_mfma_f32_16x16x32_bf16 v[118:121], v[186:189], v[204:207], v[118:121]
	v_mfma_f32_16x16x32_bf16 v[106:109], v[178:181], v[212:215], v[106:109]
	v_mfma_f32_16x16x32_bf16 v[102:105], v[186:189], v[212:215], v[102:105]
	v_mfma_f32_16x16x32_bf16 v[90:93], v[178:181], v[224:227], v[90:93]
	v_mfma_f32_16x16x32_bf16 v[86:89], v[186:189], v[224:227], v[86:89]
	s_setprio 0
	ds_read_b128 v[190:193], v171 offset:49152
	ds_read_b128 v[196:199], v171 offset:50176
	ds_read_b128 v[200:203], v171 offset:51200
	ds_read_b128 v[204:207], v171 offset:52224
	ds_read_b128 v[208:211], v171 offset:53248
	ds_read_b128 v[212:215], v171 offset:54272
	ds_read_b128 v[220:223], v171 offset:55296
	ds_read_b128 v[224:227], v171 offset:56320
	s_add_u32 s0, s90, 0x80
	s_addc_u32 s1, s91, 0
	s_add_u32 vcc_lo, s0, 0x100000
	s_addc_u32 vcc_hi, s1, 0
	s_add_i32 m0, s27, 0x18000
	s_nop 0
	global_load_lds_dwordx4 v136, s[0:1]
	s_add_i32 m0, s27, 0x1a000
	s_nop 0
	global_load_lds_dwordx4 v140, s[0:1]
	s_add_i32 m0, s27, 0x1c000
	s_nop 0
	global_load_lds_dwordx4 v136, vcc
	s_add_i32 m0, s27, 0x1e000
	s_nop 0
	global_load_lds_dwordx4 v140, vcc
	s_sleep 2
	s_waitcnt lgkmcnt(0)
	s_waitcnt vmcnt(6)
	s_barrier
	s_setprio 2
	v_mfma_f32_16x16x32_bf16 v[82:85], v[150:153], v[190:193], v[82:85]
	v_mfma_f32_16x16x32_bf16 v[78:81], v[158:161], v[190:193], v[78:81]
	v_mfma_f32_16x16x32_bf16 v[66:69], v[150:153], v[200:203], v[66:69]
	v_mfma_f32_16x16x32_bf16 v[62:65], v[158:161], v[200:203], v[62:65]
	v_mfma_f32_16x16x32_bf16 v[42:45], v[150:153], v[208:211], v[42:45]
	v_mfma_f32_16x16x32_bf16 v[34:37], v[158:161], v[208:211], v[34:37]
	v_mfma_f32_16x16x32_bf16 v[18:21], v[150:153], v[220:223], v[18:21]
	v_mfma_f32_16x16x32_bf16 v[14:17], v[158:161], v[220:223], v[14:17]
	v_mfma_f32_16x16x32_bf16 v[82:85], v[154:157], v[196:199], v[82:85]
	v_mfma_f32_16x16x32_bf16 v[78:81], v[162:165], v[196:199], v[78:81]
	v_mfma_f32_16x16x32_bf16 v[66:69], v[154:157], v[204:207], v[66:69]
	v_mfma_f32_16x16x32_bf16 v[62:65], v[162:165], v[204:207], v[62:65]
	v_mfma_f32_16x16x32_bf16 v[42:45], v[154:157], v[212:215], v[42:45]
	v_mfma_f32_16x16x32_bf16 v[34:37], v[162:165], v[212:215], v[34:37]
	v_mfma_f32_16x16x32_bf16 v[18:21], v[154:157], v[224:227], v[18:21]
	v_mfma_f32_16x16x32_bf16 v[14:17], v[162:165], v[224:227], v[14:17]
	v_mfma_f32_16x16x32_bf16 v[74:77], v[174:177], v[190:193], v[74:77]
	v_mfma_f32_16x16x32_bf16 v[70:73], v[182:185], v[190:193], v[70:73]
	v_mfma_f32_16x16x32_bf16 v[58:61], v[174:177], v[200:203], v[58:61]
	v_mfma_f32_16x16x32_bf16 v[54:57], v[182:185], v[200:203], v[54:57]
	v_mfma_f32_16x16x32_bf16 v[26:29], v[174:177], v[208:211], v[26:29]
	v_mfma_f32_16x16x32_bf16 v[22:25], v[182:185], v[208:211], v[22:25]
	v_mfma_f32_16x16x32_bf16 v[8:11], v[174:177], v[220:223], v[10:13]
	v_mfma_f32_16x16x32_bf16 v[4:7], v[182:185], v[220:223], v[4:7]
	v_mfma_f32_16x16x32_bf16 v[74:77], v[178:181], v[196:199], v[74:77]
	v_mfma_f32_16x16x32_bf16 v[70:73], v[186:189], v[196:199], v[70:73]
	v_mfma_f32_16x16x32_bf16 v[58:61], v[178:181], v[204:207], v[58:61]
	v_mfma_f32_16x16x32_bf16 v[54:57], v[186:189], v[204:207], v[54:57]
	v_mfma_f32_16x16x32_bf16 v[26:29], v[178:181], v[212:215], v[26:29]
	v_mfma_f32_16x16x32_bf16 v[22:25], v[186:189], v[212:215], v[22:25]
	v_mfma_f32_16x16x32_bf16 v[10:13], v[178:181], v[224:227], v[8:11]
	v_mfma_f32_16x16x32_bf16 v[6:9], v[186:189], v[224:227], v[4:7]
	s_setprio 0
	s_add_i32 s23, s23, 2
	s_add_u32 s88, s88, 0x100
	s_addc_u32 s89, s89, 0
	s_add_u32 s9, s9, 0x100
	s_addc_u32 s21, s21, 0
	s_cmp_gt_u32 s23, 61
	s_cbranch_scc0 .Lip_h1
.Lip_exit:
	s_and_b64 vcc, exec, s[18:19]
	s_cbranch_vccz .LBB0_352

; #define PG8_BAR __builtin_amdgcn_s_barrier()
; template <class Epi, class Sched, bool ALIGN_EPI = false, bool SP2 = false>
; __device__ __forceinline__ void gemm_phase(PG8_LAS unsigned char* lds, const Gemm g, const Sched& S, const Epi& E) {
;     ...
;         cur = nxt; cA = nA; cB = nB; ++ui;
;         if constexpr (ALIGN_EPI) { if (wr == 1) PG8_BAR; }
;     }
.LBB0_420:
	s_and_b64 vcc, exec, s[6:7]
	s_mov_b64 s[6:7], -1
	s_cbranch_vccnz .LBB0_340
	s_andn2_b64 vcc, exec, s[14:15]
	s_cbranch_vccnz .LBB0_339
	s_branch .LBB0_339
